# P0 k-scale loads hoisted out of the per-step waits; P6: waves 6-7 of non-scan workgroups run the weight conversions before the attention
# baseline (speedup 1.0000x reference)
; __device__ __forceinline__ int lane_opaque() { int l; asm volatile("v_mbcnt_lo_u32_b32 %0, -1, 0\n\tv_mbcnt_hi_u32_b32 %0, -1, %0" : "=v"(l)); return l; }
; #define LAS __attribute__((address_space(3)))
; DI void scan_attn_phase(const float* const* in, unsigned char* ws, float* y, LAS unsigned char* lds, LAS unsigned char* lds_all, LAS unsigned* ctr, int wave) {
;     ...
;     LAS unsigned char* mine = lds_all + wave * 16384;
;     attn_worker(ws, mine, ctr + 4, wave);
;     { const int lane = lane_opaque(); LAS unsigned* tile = (LAS unsigned*)mine; unsigned* cq = (unsigned*)(ws + WS_CTL) + CW_ATTQ + 64 * 8;
;         bf16* w13a = (bf16*)((unsigned char*)y + (size_t)128 * MiB);
;         for (;;) { unsigned v_ = 0u; if (lane == 0) v_ = __hip_atomic_fetch_add(cq, 2u, __ATOMIC_RELAXED, __HIP_MEMORY_SCOPE_AGENT);
;             const int it = __builtin_amdgcn_readfirstlane((int)v_); if (it >= W2_NITEMS + W13A_NITEMS) break;
;             if (it < W2_NITEMS) { convert_w2_item(in, ws, tile, it, lane); convert_w2_item(in, ws, tile, it + 1, lane); }
;             else { const int i = it - W2_NITEMS; convert_w13_item(in, ws, w13a, tile, i / (W13_SPLIT / 64), i % (W13_SPLIT / 64), lane); convert_w13_item(in, ws, w13a, tile, (i + 1) / (W13_SPLIT / 64), (i + 1) % (W13_SPLIT / 64), lane); } } }
.LBB0_2259:
	v_readlane_b32 s98, v254, 0
	v_readlane_b32 s99, v254, 2
	s_nop 1
	s_bfe_u32 s98, s98, 0x20003
	s_cmp_lg_u32 s98, 0
	s_cselect_b32 s98, 1, 0
	s_cmp_ge_u32 s99, 6
	s_cselect_b32 s98, s98, 0
	s_cmp_eq_u32 s98, 0
	s_cbranch_scc1 .Lp6_attn
	v_readlane_b32 s0, v254, 7
	v_readlane_b32 s1, v254, 8
	s_load_dwordx8 s[4:11], s[0:1], 0xc8
	s_waitcnt lgkmcnt(0)
	v_writelane_b32 v253, s4, 47
	v_writelane_b32 v253, s5, 48
	v_writelane_b32 v253, s6, 49
	v_writelane_b32 v253, s7, 50
	v_writelane_b32 v253, s8, 51
	v_writelane_b32 v253, s9, 52
	v_writelane_b32 v253, s10, 53
	v_writelane_b32 v253, s11, 54
	s_branch .LBB0_2284

; __device__ __forceinline__ int lane_opaque() { int l; asm volatile("v_mbcnt_lo_u32_b32 %0, -1, 0\n\tv_mbcnt_hi_u32_b32 %0, -1, %0" : "=v"(l)); return l; }
; #define LAS __attribute__((address_space(3)))
; DI void scan_attn_phase(const float* const* in, unsigned char* ws, float* y, LAS unsigned char* lds, LAS unsigned char* lds_all, LAS unsigned* ctr, int wave) {
;     ...
;     LAS unsigned char* mine = lds_all + wave * 16384;
;     attn_worker(ws, mine, ctr + 4, wave);
;     { const int lane = lane_opaque(); LAS unsigned* tile = (LAS unsigned*)mine; unsigned* cq = (unsigned*)(ws + WS_CTL) + CW_ATTQ + 64 * 8;
;         bf16* w13a = (bf16*)((unsigned char*)y + (size_t)128 * MiB);
;         for (;;) { unsigned v_ = 0u; if (lane == 0) v_ = __hip_atomic_fetch_add(cq, 2u, __ATOMIC_RELAXED, __HIP_MEMORY_SCOPE_AGENT);
;             const int it = __builtin_amdgcn_readfirstlane((int)v_); if (it >= W2_NITEMS + W13A_NITEMS) break;
;             if (it < W2_NITEMS) { convert_w2_item(in, ws, tile, it, lane); convert_w2_item(in, ws, tile, it + 1, lane); }
;             else { const int i = it - W2_NITEMS; convert_w13_item(in, ws, w13a, tile, i / (W13_SPLIT / 64), i % (W13_SPLIT / 64), lane); convert_w13_item(in, ws, w13a, tile, (i + 1) / (W13_SPLIT / 64), (i + 1) % (W13_SPLIT / 64), lane); } } }
.Lp6_conv_done:
	s_cmp_eq_u32 s98, 0
	s_cbranch_scc1 .LBB0_2472
	s_mov_b32 s98, 0
	v_readlane_b32 s75, v254, 0
	s_nop 1
	s_and_b32 s75, s75, 7
	s_branch .Lp6_attn
